# GEMM K-loops: global loads interleaved between first MFMA groups, last K-step peeled
# speedup vs baseline: 1.0176x; 1.0020x over previous
.LBB0_680:
	s_waitcnt lgkmcnt(3)
	v_mfma_f32_16x16x32_bf16 v[174:177], v[178:181], v[194:197], v[174:177]
	v_mfma_f32_16x16x32_bf16 v[170:173], v[178:181], v[198:201], v[170:173]
	v_mfma_f32_16x16x32_bf16 v[166:169], v[178:181], v[218:221], v[166:169]
	v_mfma_f32_16x16x32_bf16 v[158:161], v[178:181], v[238:241], v[158:161]
	s_add_u32 s100, s38, 0x1c3c000
	s_addc_u32 s101, s39, 0
	global_load_dwordx4 v[98:101], v208, s[100:101] offset:128
	v_add_u32_e32 v102, 0x10000, v208
	global_load_dwordx4 v[102:105], v102, s[100:101] offset:128
	ds_read_b128 v[202:205], v216 offset:8192
	s_waitcnt lgkmcnt(3)
	v_mfma_f32_16x16x32_bf16 v[162:165], v[182:185], v[194:197], v[162:165]
	v_mfma_f32_16x16x32_bf16 v[154:157], v[182:185], v[198:201], v[154:157]
	v_mfma_f32_16x16x32_bf16 v[134:137], v[182:185], v[218:221], v[134:137]
	v_mfma_f32_16x16x32_bf16 v[114:117], v[182:185], v[238:241], v[114:117]
	v_add_u32_e32 v106, 0x20000, v208
	global_load_dwordx4 v[106:109], v106, s[100:101] offset:128
	v_add_u32_e32 v110, 0x30000, v208
	global_load_dwordx4 v[110:113], v110, s[100:101] offset:128
	v_add_u32_e32 v217, v214, v212
	ds_read_b128 v[242:245], v216 offset:10240
	ds_read_b128 v[178:181], v217 offset:32768
	s_waitcnt lgkmcnt(4)
	v_mfma_f32_16x16x32_bf16 v[94:97], v[186:189], v[194:197], v[94:97]
	v_mfma_f32_16x16x32_bf16 v[90:93], v[186:189], v[198:201], v[90:93]
	v_mfma_f32_16x16x32_bf16 v[86:89], v[186:189], v[218:221], v[86:89]
	v_mfma_f32_16x16x32_bf16 v[82:85], v[186:189], v[238:241], v[82:85]
	v_add_u32_e32 v118, 0x40000, v208
	global_load_dwordx4 v[118:121], v118, s[100:101] offset:128
	v_add_u32_e32 v122, 0x50000, v208
	global_load_dwordx4 v[122:125], v122, s[100:101] offset:128
	ds_read_b128 v[246:249], v216 offset:12288
	ds_read_b128 v[182:185], v217 offset:34816
	s_waitcnt lgkmcnt(5)
	v_mfma_f32_16x16x32_bf16 v[78:81], v[190:193], v[194:197], v[78:81]
	v_mfma_f32_16x16x32_bf16 v[74:77], v[190:193], v[198:201], v[74:77]
	v_mfma_f32_16x16x32_bf16 v[70:73], v[190:193], v[218:221], v[70:73]
	v_mfma_f32_16x16x32_bf16 v[66:69], v[190:193], v[238:241], v[66:69]
	v_add_u32_e32 v138, 0x60000, v208
	global_load_dwordx4 v[138:141], v138, s[100:101] offset:128
	v_add_u32_e32 v142, 0x70000, v208
	global_load_dwordx4 v[142:145], v142, s[100:101] offset:128
	ds_read_b128 v[226:229], v216 offset:14336
	ds_read_b128 v[186:189], v217 offset:36864
	s_waitcnt lgkmcnt(6)
	v_mfma_f32_16x16x32_bf16 v[62:65], v[202:205], v[194:197], v[62:65]
	v_mfma_f32_16x16x32_bf16 v[58:61], v[202:205], v[198:201], v[58:61]
	v_mfma_f32_16x16x32_bf16 v[54:57], v[202:205], v[218:221], v[54:57]
	v_mfma_f32_16x16x32_bf16 v[50:53], v[202:205], v[238:241], v[50:53]
	s_add_u32 s100, s40, 0xac3c000
	s_addc_u32 s101, s41, 0
	global_load_dwordx4 v[126:129], v208, s[100:101] offset:128
	v_add_u32_e32 v130, 0x10000, v208
	global_load_dwordx4 v[130:133], v130, s[100:101] offset:128
	v_add_u32_e32 v216, v213, v212
	s_waitcnt lgkmcnt(5)
	v_mfma_f32_16x16x32_bf16 v[46:49], v[242:245], v[194:197], v[46:49]
	v_mfma_f32_16x16x32_bf16 v[42:45], v[242:245], v[198:201], v[42:45]
	v_mfma_f32_16x16x32_bf16 v[38:41], v[242:245], v[218:221], v[38:41]
	v_mfma_f32_16x16x32_bf16 v[34:37], v[242:245], v[238:241], v[34:37]
	v_add_u32_e32 v146, 0x20000, v208
	global_load_dwordx4 v[146:149], v146, s[100:101] offset:128
	v_add_u32_e32 v150, 0x30000, v208
	global_load_dwordx4 v[150:153], v150, s[100:101] offset:128
	ds_read_b128 v[242:245], v216
	ds_read_b128 v[190:193], v217 offset:38912
	ds_read_b128 v[202:205], v216 offset:2048
	s_waitcnt lgkmcnt(6)
	v_mfma_f32_16x16x32_bf16 v[30:33], v[246:249], v[194:197], v[30:33]
	v_mfma_f32_16x16x32_bf16 v[26:29], v[246:249], v[198:201], v[26:29]
	v_mfma_f32_16x16x32_bf16 v[18:21], v[246:249], v[218:221], v[18:21]
	v_mfma_f32_16x16x32_bf16 v[6:9], v[246:249], v[238:241], v[6:9]
	s_waitcnt lgkmcnt(4)
	v_mfma_f32_16x16x32_bf16 v[14:17], v[226:229], v[198:201], v[14:17]
	ds_read_b128 v[198:201], v216 offset:4096
	v_mfma_f32_16x16x32_bf16 v[22:25], v[226:229], v[194:197], v[22:25]
	v_mfma_f32_16x16x32_bf16 v[10:13], v[226:229], v[218:221], v[10:13]
	v_mfma_f32_16x16x32_bf16 v[2:5], v[226:229], v[238:241], v[2:5]
	ds_read_b128 v[194:197], v216 offset:6144
	s_waitcnt lgkmcnt(4)
	v_mfma_f32_16x16x32_bf16 v[174:177], v[242:245], v[178:181], v[174:177]
	v_mfma_f32_16x16x32_bf16 v[170:173], v[242:245], v[182:185], v[170:173]
	v_mfma_f32_16x16x32_bf16 v[166:169], v[242:245], v[186:189], v[166:169]
	s_waitcnt lgkmcnt(3)
	v_mfma_f32_16x16x32_bf16 v[158:161], v[242:245], v[190:193], v[158:161]
	s_branch .LBB0_677
.Lpeel_677:
	s_waitcnt lgkmcnt(3)
	v_mfma_f32_16x16x32_bf16 v[174:177], v[178:181], v[194:197], v[174:177]
	v_mfma_f32_16x16x32_bf16 v[170:173], v[178:181], v[198:201], v[170:173]
	v_mfma_f32_16x16x32_bf16 v[166:169], v[178:181], v[218:221], v[166:169]
	v_mfma_f32_16x16x32_bf16 v[158:161], v[178:181], v[238:241], v[158:161]
	ds_read_b128 v[202:205], v216 offset:8192
	s_waitcnt lgkmcnt(3)
	v_mfma_f32_16x16x32_bf16 v[162:165], v[182:185], v[194:197], v[162:165]
	v_mfma_f32_16x16x32_bf16 v[154:157], v[182:185], v[198:201], v[154:157]
	v_mfma_f32_16x16x32_bf16 v[134:137], v[182:185], v[218:221], v[134:137]
	v_mfma_f32_16x16x32_bf16 v[114:117], v[182:185], v[238:241], v[114:117]
	v_add_u32_e32 v217, v214, v212
	ds_read_b128 v[242:245], v216 offset:10240
	ds_read_b128 v[178:181], v217 offset:32768
	s_waitcnt lgkmcnt(4)
	v_mfma_f32_16x16x32_bf16 v[94:97], v[186:189], v[194:197], v[94:97]
	v_mfma_f32_16x16x32_bf16 v[90:93], v[186:189], v[198:201], v[90:93]
	v_mfma_f32_16x16x32_bf16 v[86:89], v[186:189], v[218:221], v[86:89]
	v_mfma_f32_16x16x32_bf16 v[82:85], v[186:189], v[238:241], v[82:85]
	ds_read_b128 v[246:249], v216 offset:12288
	ds_read_b128 v[182:185], v217 offset:34816
	s_waitcnt lgkmcnt(5)
	v_mfma_f32_16x16x32_bf16 v[78:81], v[190:193], v[194:197], v[78:81]
	v_mfma_f32_16x16x32_bf16 v[74:77], v[190:193], v[198:201], v[74:77]
	v_mfma_f32_16x16x32_bf16 v[70:73], v[190:193], v[218:221], v[70:73]
	v_mfma_f32_16x16x32_bf16 v[66:69], v[190:193], v[238:241], v[66:69]
	ds_read_b128 v[226:229], v216 offset:14336
	ds_read_b128 v[186:189], v217 offset:36864
	s_waitcnt lgkmcnt(6)
	v_mfma_f32_16x16x32_bf16 v[62:65], v[202:205], v[194:197], v[62:65]
	v_mfma_f32_16x16x32_bf16 v[58:61], v[202:205], v[198:201], v[58:61]
	v_mfma_f32_16x16x32_bf16 v[54:57], v[202:205], v[218:221], v[54:57]
	v_mfma_f32_16x16x32_bf16 v[50:53], v[202:205], v[238:241], v[50:53]
	v_add_u32_e32 v216, v213, v212
	s_waitcnt lgkmcnt(5)
	v_mfma_f32_16x16x32_bf16 v[46:49], v[242:245], v[194:197], v[46:49]
	v_mfma_f32_16x16x32_bf16 v[42:45], v[242:245], v[198:201], v[42:45]
	v_mfma_f32_16x16x32_bf16 v[38:41], v[242:245], v[218:221], v[38:41]
	v_mfma_f32_16x16x32_bf16 v[34:37], v[242:245], v[238:241], v[34:37]
	ds_read_b128 v[242:245], v216
	ds_read_b128 v[190:193], v217 offset:38912
	ds_read_b128 v[202:205], v216 offset:2048
	s_waitcnt lgkmcnt(6)
	v_mfma_f32_16x16x32_bf16 v[30:33], v[246:249], v[194:197], v[30:33]
	v_mfma_f32_16x16x32_bf16 v[26:29], v[246:249], v[198:201], v[26:29]
	v_mfma_f32_16x16x32_bf16 v[18:21], v[246:249], v[218:221], v[18:21]
	v_mfma_f32_16x16x32_bf16 v[6:9], v[246:249], v[238:241], v[6:9]
	s_waitcnt lgkmcnt(4)
	v_mfma_f32_16x16x32_bf16 v[14:17], v[226:229], v[198:201], v[14:17]
	ds_read_b128 v[198:201], v216 offset:4096
	v_mfma_f32_16x16x32_bf16 v[22:25], v[226:229], v[194:197], v[22:25]
	v_mfma_f32_16x16x32_bf16 v[10:13], v[226:229], v[218:221], v[10:13]
	v_mfma_f32_16x16x32_bf16 v[2:5], v[226:229], v[238:241], v[2:5]
	ds_read_b128 v[194:197], v216 offset:6144
	s_waitcnt lgkmcnt(4)
	v_mfma_f32_16x16x32_bf16 v[174:177], v[242:245], v[178:181], v[174:177]
	v_mfma_f32_16x16x32_bf16 v[170:173], v[242:245], v[182:185], v[170:173]
	v_mfma_f32_16x16x32_bf16 v[166:169], v[242:245], v[186:189], v[166:169]
	s_waitcnt lgkmcnt(3)
	v_mfma_f32_16x16x32_bf16 v[158:161], v[242:245], v[190:193], v[158:161]
	s_add_i32 s10, s10, 64
	s_waitcnt lgkmcnt(2)
	v_mfma_f32_16x16x32_bf16 v[162:165], v[202:205], v[178:181], v[162:165]
	v_mfma_f32_16x16x32_bf16 v[154:157], v[202:205], v[182:185], v[154:157]
	v_mfma_f32_16x16x32_bf16 v[134:137], v[202:205], v[186:189], v[134:137]
	v_mfma_f32_16x16x32_bf16 v[114:117], v[202:205], v[190:193], v[114:117]
	ds_read_b128 v[202:205], v216 offset:8192
	s_waitcnt lgkmcnt(2)
	v_mfma_f32_16x16x32_bf16 v[94:97], v[198:201], v[178:181], v[94:97]
	v_mfma_f32_16x16x32_bf16 v[90:93], v[198:201], v[182:185], v[90:93]
	v_mfma_f32_16x16x32_bf16 v[86:89], v[198:201], v[186:189], v[86:89]
	v_mfma_f32_16x16x32_bf16 v[82:85], v[198:201], v[190:193], v[82:85]
	ds_read_b128 v[198:201], v216 offset:10240
	s_waitcnt lgkmcnt(2)
	v_mfma_f32_16x16x32_bf16 v[78:81], v[194:197], v[178:181], v[78:81]
	v_mfma_f32_16x16x32_bf16 v[74:77], v[194:197], v[182:185], v[74:77]
	v_mfma_f32_16x16x32_bf16 v[70:73], v[194:197], v[186:189], v[70:73]
	v_mfma_f32_16x16x32_bf16 v[66:69], v[194:197], v[190:193], v[66:69]
	ds_read_b128 v[194:197], v216 offset:12288
	s_waitcnt lgkmcnt(2)
	v_mfma_f32_16x16x32_bf16 v[62:65], v[202:205], v[178:181], v[62:65]
	v_mfma_f32_16x16x32_bf16 v[58:61], v[202:205], v[182:185], v[58:61]
	v_mfma_f32_16x16x32_bf16 v[54:57], v[202:205], v[186:189], v[54:57]
	v_mfma_f32_16x16x32_bf16 v[50:53], v[202:205], v[190:193], v[50:53]
	ds_read_b128 v[202:205], v216 offset:14336
	s_waitcnt lgkmcnt(2)
	v_mfma_f32_16x16x32_bf16 v[46:49], v[198:201], v[178:181], v[46:49]
	v_mfma_f32_16x16x32_bf16 v[42:45], v[198:201], v[182:185], v[42:45]
	v_mfma_f32_16x16x32_bf16 v[38:41], v[198:201], v[186:189], v[38:41]
	v_mfma_f32_16x16x32_bf16 v[34:37], v[198:201], v[190:193], v[34:37]
	s_waitcnt lgkmcnt(1)
	v_mfma_f32_16x16x32_bf16 v[30:33], v[194:197], v[178:181], v[30:33]
	v_mfma_f32_16x16x32_bf16 v[26:29], v[194:197], v[182:185], v[26:29]
	v_mfma_f32_16x16x32_bf16 v[18:21], v[194:197], v[186:189], v[18:21]
	v_mfma_f32_16x16x32_bf16 v[6:9], v[194:197], v[190:193], v[6:9]
	s_waitcnt lgkmcnt(0)
	v_mfma_f32_16x16x32_bf16 v[22:25], v[202:205], v[178:181], v[22:25]
	v_mfma_f32_16x16x32_bf16 v[14:17], v[202:205], v[182:185], v[14:17]
	v_mfma_f32_16x16x32_bf16 v[10:13], v[202:205], v[186:189], v[10:13]
	v_mfma_f32_16x16x32_bf16 v[2:5], v[202:205], v[190:193], v[2:5]
	s_setprio 0
	s_branch .LBB0_684

.LBB0_1486:
	s_waitcnt lgkmcnt(3)
	v_mfma_f32_16x16x32_bf16 v[174:177], v[178:181], v[194:197], v[174:177]
	v_mfma_f32_16x16x32_bf16 v[170:173], v[178:181], v[198:201], v[170:173]
	v_mfma_f32_16x16x32_bf16 v[166:169], v[178:181], v[218:221], v[166:169]
	v_mfma_f32_16x16x32_bf16 v[158:161], v[178:181], v[226:229], v[158:161]
	s_add_u32 s100, s38, 0x1c3c000
	s_addc_u32 s101, s39, 0
	global_load_dwordx4 v[98:101], v208, s[100:101] offset:128
	v_add_u32_e32 v102, 0x10000, v208
	global_load_dwordx4 v[102:105], v102, s[100:101] offset:128
	ds_read_b128 v[202:205], v216 offset:8192
	s_waitcnt lgkmcnt(3)
	v_mfma_f32_16x16x32_bf16 v[162:165], v[182:185], v[194:197], v[162:165]
	v_mfma_f32_16x16x32_bf16 v[154:157], v[182:185], v[198:201], v[154:157]
	v_mfma_f32_16x16x32_bf16 v[122:125], v[182:185], v[218:221], v[122:125]
	v_mfma_f32_16x16x32_bf16 v[106:109], v[182:185], v[226:229], v[106:109]
	v_add_u32_e32 v110, 0x20000, v208
	global_load_dwordx4 v[110:113], v110, s[100:101] offset:128
	v_add_u32_e32 v114, 0x30000, v208
	global_load_dwordx4 v[114:117], v114, s[100:101] offset:128
	v_add_u32_e32 v217, v214, v212
	ds_read_b128 v[238:241], v216 offset:10240
	ds_read_b128 v[178:181], v217 offset:32768
	s_waitcnt lgkmcnt(4)
	v_mfma_f32_16x16x32_bf16 v[94:97], v[186:189], v[194:197], v[94:97]
	v_mfma_f32_16x16x32_bf16 v[90:93], v[186:189], v[198:201], v[90:93]
	v_mfma_f32_16x16x32_bf16 v[86:89], v[186:189], v[218:221], v[86:89]
	v_mfma_f32_16x16x32_bf16 v[82:85], v[186:189], v[226:229], v[82:85]
	v_add_u32_e32 v118, 0x40000, v208
	global_load_dwordx4 v[118:121], v118, s[100:101] offset:128
	v_add_u32_e32 v130, 0x50000, v208
	global_load_dwordx4 v[130:133], v130, s[100:101] offset:128
	ds_read_b128 v[242:245], v216 offset:12288
	ds_read_b128 v[182:185], v217 offset:34816
	s_waitcnt lgkmcnt(5)
	v_mfma_f32_16x16x32_bf16 v[78:81], v[190:193], v[194:197], v[78:81]
	v_mfma_f32_16x16x32_bf16 v[74:77], v[190:193], v[198:201], v[74:77]
	v_mfma_f32_16x16x32_bf16 v[70:73], v[190:193], v[218:221], v[70:73]
	v_mfma_f32_16x16x32_bf16 v[66:69], v[190:193], v[226:229], v[66:69]
	v_add_u32_e32 v138, 0x60000, v208
	global_load_dwordx4 v[138:141], v138, s[100:101] offset:128
	v_add_u32_e32 v146, 0x70000, v208
	global_load_dwordx4 v[146:149], v146, s[100:101] offset:128
	ds_read_b128 v[246:249], v216 offset:14336
	ds_read_b128 v[186:189], v217 offset:36864
	s_waitcnt lgkmcnt(6)
	v_mfma_f32_16x16x32_bf16 v[62:65], v[202:205], v[194:197], v[62:65]
	v_mfma_f32_16x16x32_bf16 v[58:61], v[202:205], v[198:201], v[58:61]
	v_mfma_f32_16x16x32_bf16 v[54:57], v[202:205], v[218:221], v[54:57]
	v_mfma_f32_16x16x32_bf16 v[50:53], v[202:205], v[226:229], v[50:53]
	s_add_u32 s100, s40, 0xb34c000
	s_addc_u32 s101, s41, 0
	global_load_dwordx4 v[126:129], v208, s[100:101] offset:128
	v_add_u32_e32 v134, 0x10000, v208
	global_load_dwordx4 v[134:137], v134, s[100:101] offset:128
	v_add_u32_e32 v216, v213, v212
	s_waitcnt lgkmcnt(5)
	v_mfma_f32_16x16x32_bf16 v[46:49], v[238:241], v[194:197], v[46:49]
	v_mfma_f32_16x16x32_bf16 v[42:45], v[238:241], v[198:201], v[42:45]
	v_mfma_f32_16x16x32_bf16 v[38:41], v[238:241], v[218:221], v[38:41]
	v_mfma_f32_16x16x32_bf16 v[34:37], v[238:241], v[226:229], v[34:37]
	v_add_u32_e32 v142, 0x20000, v208
	global_load_dwordx4 v[142:145], v142, s[100:101] offset:128
	v_add_u32_e32 v150, 0x30000, v208
	global_load_dwordx4 v[150:153], v150, s[100:101] offset:128
	ds_read_b128 v[238:241], v216
	ds_read_b128 v[190:193], v217 offset:38912
	ds_read_b128 v[202:205], v216 offset:2048
	s_waitcnt lgkmcnt(6)
	v_mfma_f32_16x16x32_bf16 v[30:33], v[242:245], v[194:197], v[30:33]
	v_mfma_f32_16x16x32_bf16 v[26:29], v[242:245], v[198:201], v[26:29]
	v_mfma_f32_16x16x32_bf16 v[18:21], v[242:245], v[218:221], v[18:21]
	v_mfma_f32_16x16x32_bf16 v[6:9], v[242:245], v[226:229], v[6:9]
	s_waitcnt lgkmcnt(4)
	v_mfma_f32_16x16x32_bf16 v[14:17], v[246:249], v[198:201], v[14:17]
	ds_read_b128 v[198:201], v216 offset:4096
	v_mfma_f32_16x16x32_bf16 v[22:25], v[246:249], v[194:197], v[22:25]
	v_mfma_f32_16x16x32_bf16 v[10:13], v[246:249], v[218:221], v[10:13]
	v_mfma_f32_16x16x32_bf16 v[2:5], v[246:249], v[226:229], v[2:5]
	ds_read_b128 v[194:197], v216 offset:6144
	s_waitcnt lgkmcnt(4)
	v_mfma_f32_16x16x32_bf16 v[174:177], v[238:241], v[178:181], v[174:177]
	v_mfma_f32_16x16x32_bf16 v[170:173], v[238:241], v[182:185], v[170:173]
	v_mfma_f32_16x16x32_bf16 v[166:169], v[238:241], v[186:189], v[166:169]
	s_waitcnt lgkmcnt(3)
	v_mfma_f32_16x16x32_bf16 v[158:161], v[238:241], v[190:193], v[158:161]
	s_branch .LBB0_1483
.Lpeel_1483:
	s_waitcnt lgkmcnt(3)
	v_mfma_f32_16x16x32_bf16 v[174:177], v[178:181], v[194:197], v[174:177]
	v_mfma_f32_16x16x32_bf16 v[170:173], v[178:181], v[198:201], v[170:173]
	v_mfma_f32_16x16x32_bf16 v[166:169], v[178:181], v[218:221], v[166:169]
	v_mfma_f32_16x16x32_bf16 v[158:161], v[178:181], v[226:229], v[158:161]
	ds_read_b128 v[202:205], v216 offset:8192
	s_waitcnt lgkmcnt(3)
	v_mfma_f32_16x16x32_bf16 v[162:165], v[182:185], v[194:197], v[162:165]
	v_mfma_f32_16x16x32_bf16 v[154:157], v[182:185], v[198:201], v[154:157]
	v_mfma_f32_16x16x32_bf16 v[122:125], v[182:185], v[218:221], v[122:125]
	v_mfma_f32_16x16x32_bf16 v[106:109], v[182:185], v[226:229], v[106:109]
	v_add_u32_e32 v217, v214, v212
	ds_read_b128 v[238:241], v216 offset:10240
	ds_read_b128 v[178:181], v217 offset:32768
	s_waitcnt lgkmcnt(4)
	v_mfma_f32_16x16x32_bf16 v[94:97], v[186:189], v[194:197], v[94:97]
	v_mfma_f32_16x16x32_bf16 v[90:93], v[186:189], v[198:201], v[90:93]
	v_mfma_f32_16x16x32_bf16 v[86:89], v[186:189], v[218:221], v[86:89]
	v_mfma_f32_16x16x32_bf16 v[82:85], v[186:189], v[226:229], v[82:85]
	ds_read_b128 v[242:245], v216 offset:12288
	ds_read_b128 v[182:185], v217 offset:34816
	s_waitcnt lgkmcnt(5)
	v_mfma_f32_16x16x32_bf16 v[78:81], v[190:193], v[194:197], v[78:81]
	v_mfma_f32_16x16x32_bf16 v[74:77], v[190:193], v[198:201], v[74:77]
	v_mfma_f32_16x16x32_bf16 v[70:73], v[190:193], v[218:221], v[70:73]
	v_mfma_f32_16x16x32_bf16 v[66:69], v[190:193], v[226:229], v[66:69]
	ds_read_b128 v[246:249], v216 offset:14336
	ds_read_b128 v[186:189], v217 offset:36864
	s_waitcnt lgkmcnt(6)
	v_mfma_f32_16x16x32_bf16 v[62:65], v[202:205], v[194:197], v[62:65]
	v_mfma_f32_16x16x32_bf16 v[58:61], v[202:205], v[198:201], v[58:61]
	v_mfma_f32_16x16x32_bf16 v[54:57], v[202:205], v[218:221], v[54:57]
	v_mfma_f32_16x16x32_bf16 v[50:53], v[202:205], v[226:229], v[50:53]
	v_add_u32_e32 v216, v213, v212
	s_waitcnt lgkmcnt(5)
	v_mfma_f32_16x16x32_bf16 v[46:49], v[238:241], v[194:197], v[46:49]
	v_mfma_f32_16x16x32_bf16 v[42:45], v[238:241], v[198:201], v[42:45]
	v_mfma_f32_16x16x32_bf16 v[38:41], v[238:241], v[218:221], v[38:41]
	v_mfma_f32_16x16x32_bf16 v[34:37], v[238:241], v[226:229], v[34:37]
	ds_read_b128 v[238:241], v216
	ds_read_b128 v[190:193], v217 offset:38912
	ds_read_b128 v[202:205], v216 offset:2048
	s_waitcnt lgkmcnt(6)
	v_mfma_f32_16x16x32_bf16 v[30:33], v[242:245], v[194:197], v[30:33]
	v_mfma_f32_16x16x32_bf16 v[26:29], v[242:245], v[198:201], v[26:29]
	v_mfma_f32_16x16x32_bf16 v[18:21], v[242:245], v[218:221], v[18:21]
	v_mfma_f32_16x16x32_bf16 v[6:9], v[242:245], v[226:229], v[6:9]
	s_waitcnt lgkmcnt(4)
	v_mfma_f32_16x16x32_bf16 v[14:17], v[246:249], v[198:201], v[14:17]
	ds_read_b128 v[198:201], v216 offset:4096
	v_mfma_f32_16x16x32_bf16 v[22:25], v[246:249], v[194:197], v[22:25]
	v_mfma_f32_16x16x32_bf16 v[10:13], v[246:249], v[218:221], v[10:13]
	v_mfma_f32_16x16x32_bf16 v[2:5], v[246:249], v[226:229], v[2:5]
	ds_read_b128 v[194:197], v216 offset:6144
	s_waitcnt lgkmcnt(4)
	v_mfma_f32_16x16x32_bf16 v[174:177], v[238:241], v[178:181], v[174:177]
	v_mfma_f32_16x16x32_bf16 v[170:173], v[238:241], v[182:185], v[170:173]
	v_mfma_f32_16x16x32_bf16 v[166:169], v[238:241], v[186:189], v[166:169]
	s_waitcnt lgkmcnt(3)
	v_mfma_f32_16x16x32_bf16 v[158:161], v[238:241], v[190:193], v[158:161]
	s_add_i32 s1, s1, 64
	s_waitcnt lgkmcnt(2)
	v_mfma_f32_16x16x32_bf16 v[162:165], v[202:205], v[178:181], v[162:165]
	v_mfma_f32_16x16x32_bf16 v[154:157], v[202:205], v[182:185], v[154:157]
	v_mfma_f32_16x16x32_bf16 v[122:125], v[202:205], v[186:189], v[122:125]
	v_mfma_f32_16x16x32_bf16 v[106:109], v[202:205], v[190:193], v[106:109]
	ds_read_b128 v[202:205], v216 offset:8192
	s_waitcnt lgkmcnt(2)
	v_mfma_f32_16x16x32_bf16 v[94:97], v[198:201], v[178:181], v[94:97]
	v_mfma_f32_16x16x32_bf16 v[90:93], v[198:201], v[182:185], v[90:93]
	v_mfma_f32_16x16x32_bf16 v[86:89], v[198:201], v[186:189], v[86:89]
	v_mfma_f32_16x16x32_bf16 v[82:85], v[198:201], v[190:193], v[82:85]
	ds_read_b128 v[198:201], v216 offset:10240
	s_waitcnt lgkmcnt(2)
	v_mfma_f32_16x16x32_bf16 v[78:81], v[194:197], v[178:181], v[78:81]
	v_mfma_f32_16x16x32_bf16 v[74:77], v[194:197], v[182:185], v[74:77]
	v_mfma_f32_16x16x32_bf16 v[70:73], v[194:197], v[186:189], v[70:73]
	v_mfma_f32_16x16x32_bf16 v[66:69], v[194:197], v[190:193], v[66:69]
	ds_read_b128 v[194:197], v216 offset:12288
	s_waitcnt lgkmcnt(2)
	v_mfma_f32_16x16x32_bf16 v[62:65], v[202:205], v[178:181], v[62:65]
	v_mfma_f32_16x16x32_bf16 v[58:61], v[202:205], v[182:185], v[58:61]
	v_mfma_f32_16x16x32_bf16 v[54:57], v[202:205], v[186:189], v[54:57]
	v_mfma_f32_16x16x32_bf16 v[50:53], v[202:205], v[190:193], v[50:53]
	ds_read_b128 v[202:205], v216 offset:14336
	s_waitcnt lgkmcnt(2)
	v_mfma_f32_16x16x32_bf16 v[46:49], v[198:201], v[178:181], v[46:49]
	v_mfma_f32_16x16x32_bf16 v[42:45], v[198:201], v[182:185], v[42:45]
	v_mfma_f32_16x16x32_bf16 v[38:41], v[198:201], v[186:189], v[38:41]
	v_mfma_f32_16x16x32_bf16 v[34:37], v[198:201], v[190:193], v[34:37]
	s_waitcnt lgkmcnt(1)
	v_mfma_f32_16x16x32_bf16 v[30:33], v[194:197], v[178:181], v[30:33]
	v_mfma_f32_16x16x32_bf16 v[26:29], v[194:197], v[182:185], v[26:29]
	v_mfma_f32_16x16x32_bf16 v[18:21], v[194:197], v[186:189], v[18:21]
	v_mfma_f32_16x16x32_bf16 v[6:9], v[194:197], v[190:193], v[6:9]
	s_waitcnt lgkmcnt(0)
	v_mfma_f32_16x16x32_bf16 v[22:25], v[202:205], v[178:181], v[22:25]
	v_mfma_f32_16x16x32_bf16 v[14:17], v[202:205], v[182:185], v[14:17]
	v_mfma_f32_16x16x32_bf16 v[10:13], v[202:205], v[186:189], v[10:13]
	v_mfma_f32_16x16x32_bf16 v[2:5], v[202:205], v[190:193], v[2:5]
	s_setprio 0
	s_branch .LBB0_1490

.LBB0_1684:
	s_waitcnt lgkmcnt(3)
	v_mfma_f32_16x16x32_bf16 v[114:117], v[178:181], v[194:197], v[114:117]
	v_mfma_f32_16x16x32_bf16 v[134:137], v[178:181], v[198:201], v[134:137]
	v_mfma_f32_16x16x32_bf16 v[138:141], v[178:181], v[218:221], v[138:141]
	v_mfma_f32_16x16x32_bf16 v[142:145], v[178:181], v[226:229], v[142:145]
	s_add_u32 s100, s36, 0x1c3b000
	s_addc_u32 s101, s37, 0
	global_load_dwordx4 v[2:5], v208, s[100:101] offset:2176
	v_add_u32_e32 v6, 0x10000, v208
	global_load_dwordx4 v[6:9], v6, s[100:101] offset:2176
	ds_read_b128 v[202:205], v217 offset:8192
	s_waitcnt lgkmcnt(3)
	v_mfma_f32_16x16x32_bf16 v[162:165], v[182:185], v[194:197], v[162:165]
	v_mfma_f32_16x16x32_bf16 v[166:169], v[182:185], v[198:201], v[166:169]
	v_mfma_f32_16x16x32_bf16 v[170:173], v[182:185], v[218:221], v[170:173]
	v_mfma_f32_16x16x32_bf16 v[174:177], v[182:185], v[226:229], v[174:177]
	v_add_u32_e32 v10, 0x20000, v208
	global_load_dwordx4 v[10:13], v10, s[100:101] offset:2176
	v_add_u32_e32 v14, 0x30000, v208
	global_load_dwordx4 v[14:17], v14, s[100:101] offset:2176
	v_add_u32_e32 v222, v215, v213
	ds_read_b128 v[238:241], v217 offset:10240
	ds_read_b128 v[178:181], v222 offset:32768
	s_waitcnt lgkmcnt(4)
	v_mfma_f32_16x16x32_bf16 v[146:149], v[186:189], v[194:197], v[146:149]
	v_mfma_f32_16x16x32_bf16 v[150:153], v[186:189], v[198:201], v[150:153]
	v_mfma_f32_16x16x32_bf16 v[154:157], v[186:189], v[218:221], v[154:157]
	v_mfma_f32_16x16x32_bf16 v[158:161], v[186:189], v[226:229], v[158:161]
	v_add_u32_e32 v18, 0x40000, v208
	global_load_dwordx4 v[18:21], v18, s[100:101] offset:2176
	v_add_u32_e32 v26, 0x50000, v208
	global_load_dwordx4 v[26:29], v26, s[100:101] offset:2176
	ds_read_b128 v[242:245], v217 offset:12288
	ds_read_b128 v[182:185], v222 offset:34816
	s_waitcnt lgkmcnt(5)
	v_mfma_f32_16x16x32_bf16 v[118:121], v[190:193], v[194:197], v[118:121]
	v_mfma_f32_16x16x32_bf16 v[122:125], v[190:193], v[198:201], v[122:125]
	v_mfma_f32_16x16x32_bf16 v[126:129], v[190:193], v[218:221], v[126:129]
	v_mfma_f32_16x16x32_bf16 v[130:133], v[190:193], v[226:229], v[130:133]
	v_add_u32_e32 v34, 0x60000, v208
	global_load_dwordx4 v[34:37], v34, s[100:101] offset:2176
	v_add_u32_e32 v42, 0x70000, v208
	global_load_dwordx4 v[42:45], v42, s[100:101] offset:2176
	ds_read_b128 v[246:249], v217 offset:14336
	ds_read_b128 v[186:189], v222 offset:36864
	s_waitcnt lgkmcnt(6)
	v_mfma_f32_16x16x32_bf16 v[98:101], v[202:205], v[194:197], v[98:101]
	v_mfma_f32_16x16x32_bf16 v[102:105], v[202:205], v[198:201], v[102:105]
	v_mfma_f32_16x16x32_bf16 v[106:109], v[202:205], v[218:221], v[106:109]
	v_mfma_f32_16x16x32_bf16 v[110:113], v[202:205], v[226:229], v[110:113]
	s_add_u32 s100, s38, 0xb54c000
	s_addc_u32 s101, s39, 0
	global_load_dwordx4 v[22:25], v208, s[100:101] offset:128
	v_add_u32_e32 v30, 0x10000, v208
	global_load_dwordx4 v[30:33], v30, s[100:101] offset:128
	v_add_u32_e32 v217, v214, v213
	s_waitcnt lgkmcnt(5)
	v_mfma_f32_16x16x32_bf16 v[82:85], v[238:241], v[194:197], v[82:85]
	v_mfma_f32_16x16x32_bf16 v[86:89], v[238:241], v[198:201], v[86:89]
	v_mfma_f32_16x16x32_bf16 v[90:93], v[238:241], v[218:221], v[90:93]
	v_mfma_f32_16x16x32_bf16 v[94:97], v[238:241], v[226:229], v[94:97]
	v_add_u32_e32 v38, 0x20000, v208
	global_load_dwordx4 v[38:41], v38, s[100:101] offset:128
	v_add_u32_e32 v46, 0x30000, v208
	global_load_dwordx4 v[46:49], v46, s[100:101] offset:128
	ds_read_b128 v[238:241], v217
	ds_read_b128 v[190:193], v222 offset:38912
	ds_read_b128 v[202:205], v217 offset:2048
	s_waitcnt lgkmcnt(6)
	v_mfma_f32_16x16x32_bf16 v[66:69], v[242:245], v[194:197], v[66:69]
	v_mfma_f32_16x16x32_bf16 v[70:73], v[242:245], v[198:201], v[70:73]
	v_mfma_f32_16x16x32_bf16 v[74:77], v[242:245], v[218:221], v[74:77]
	v_mfma_f32_16x16x32_bf16 v[78:81], v[242:245], v[226:229], v[78:81]
	s_waitcnt lgkmcnt(4)
	v_mfma_f32_16x16x32_bf16 v[54:57], v[246:249], v[198:201], v[54:57]
	ds_read_b128 v[198:201], v217 offset:4096
	v_mfma_f32_16x16x32_bf16 v[50:53], v[246:249], v[194:197], v[50:53]
	v_mfma_f32_16x16x32_bf16 v[58:61], v[246:249], v[218:221], v[58:61]
	v_mfma_f32_16x16x32_bf16 v[62:65], v[246:249], v[226:229], v[62:65]
	ds_read_b128 v[194:197], v217 offset:6144
	s_waitcnt lgkmcnt(4)
	v_mfma_f32_16x16x32_bf16 v[114:117], v[238:241], v[178:181], v[114:117]
	v_mfma_f32_16x16x32_bf16 v[134:137], v[238:241], v[182:185], v[134:137]
	v_mfma_f32_16x16x32_bf16 v[138:141], v[238:241], v[186:189], v[138:141]
	s_waitcnt lgkmcnt(3)
	v_mfma_f32_16x16x32_bf16 v[142:145], v[238:241], v[190:193], v[142:145]
	s_branch .LBB0_1681
.Lpeel_1681:
	s_waitcnt lgkmcnt(3)
	v_mfma_f32_16x16x32_bf16 v[114:117], v[178:181], v[194:197], v[114:117]
	v_mfma_f32_16x16x32_bf16 v[134:137], v[178:181], v[198:201], v[134:137]
	v_mfma_f32_16x16x32_bf16 v[138:141], v[178:181], v[218:221], v[138:141]
	v_mfma_f32_16x16x32_bf16 v[142:145], v[178:181], v[226:229], v[142:145]
	ds_read_b128 v[202:205], v217 offset:8192
	s_waitcnt lgkmcnt(3)
	v_mfma_f32_16x16x32_bf16 v[162:165], v[182:185], v[194:197], v[162:165]
	v_mfma_f32_16x16x32_bf16 v[166:169], v[182:185], v[198:201], v[166:169]
	v_mfma_f32_16x16x32_bf16 v[170:173], v[182:185], v[218:221], v[170:173]
	v_mfma_f32_16x16x32_bf16 v[174:177], v[182:185], v[226:229], v[174:177]
	v_add_u32_e32 v222, v215, v213
	ds_read_b128 v[238:241], v217 offset:10240
	ds_read_b128 v[178:181], v222 offset:32768
	s_waitcnt lgkmcnt(4)
	v_mfma_f32_16x16x32_bf16 v[146:149], v[186:189], v[194:197], v[146:149]
	v_mfma_f32_16x16x32_bf16 v[150:153], v[186:189], v[198:201], v[150:153]
	v_mfma_f32_16x16x32_bf16 v[154:157], v[186:189], v[218:221], v[154:157]
	v_mfma_f32_16x16x32_bf16 v[158:161], v[186:189], v[226:229], v[158:161]
	ds_read_b128 v[242:245], v217 offset:12288
	ds_read_b128 v[182:185], v222 offset:34816
	s_waitcnt lgkmcnt(5)
	v_mfma_f32_16x16x32_bf16 v[118:121], v[190:193], v[194:197], v[118:121]
	v_mfma_f32_16x16x32_bf16 v[122:125], v[190:193], v[198:201], v[122:125]
	v_mfma_f32_16x16x32_bf16 v[126:129], v[190:193], v[218:221], v[126:129]
	v_mfma_f32_16x16x32_bf16 v[130:133], v[190:193], v[226:229], v[130:133]
	ds_read_b128 v[246:249], v217 offset:14336
	ds_read_b128 v[186:189], v222 offset:36864
	s_waitcnt lgkmcnt(6)
	v_mfma_f32_16x16x32_bf16 v[98:101], v[202:205], v[194:197], v[98:101]
	v_mfma_f32_16x16x32_bf16 v[102:105], v[202:205], v[198:201], v[102:105]
	v_mfma_f32_16x16x32_bf16 v[106:109], v[202:205], v[218:221], v[106:109]
	v_mfma_f32_16x16x32_bf16 v[110:113], v[202:205], v[226:229], v[110:113]
	v_add_u32_e32 v217, v214, v213
	s_waitcnt lgkmcnt(5)
	v_mfma_f32_16x16x32_bf16 v[82:85], v[238:241], v[194:197], v[82:85]
	v_mfma_f32_16x16x32_bf16 v[86:89], v[238:241], v[198:201], v[86:89]
	v_mfma_f32_16x16x32_bf16 v[90:93], v[238:241], v[218:221], v[90:93]
	v_mfma_f32_16x16x32_bf16 v[94:97], v[238:241], v[226:229], v[94:97]
	ds_read_b128 v[238:241], v217
	ds_read_b128 v[190:193], v222 offset:38912
	ds_read_b128 v[202:205], v217 offset:2048
	s_waitcnt lgkmcnt(6)
	v_mfma_f32_16x16x32_bf16 v[66:69], v[242:245], v[194:197], v[66:69]
	v_mfma_f32_16x16x32_bf16 v[70:73], v[242:245], v[198:201], v[70:73]
	v_mfma_f32_16x16x32_bf16 v[74:77], v[242:245], v[218:221], v[74:77]
	v_mfma_f32_16x16x32_bf16 v[78:81], v[242:245], v[226:229], v[78:81]
	s_waitcnt lgkmcnt(4)
	v_mfma_f32_16x16x32_bf16 v[54:57], v[246:249], v[198:201], v[54:57]
	ds_read_b128 v[198:201], v217 offset:4096
	v_mfma_f32_16x16x32_bf16 v[50:53], v[246:249], v[194:197], v[50:53]
	v_mfma_f32_16x16x32_bf16 v[58:61], v[246:249], v[218:221], v[58:61]
	v_mfma_f32_16x16x32_bf16 v[62:65], v[246:249], v[226:229], v[62:65]
	ds_read_b128 v[194:197], v217 offset:6144
	s_waitcnt lgkmcnt(4)
	v_mfma_f32_16x16x32_bf16 v[114:117], v[238:241], v[178:181], v[114:117]
	v_mfma_f32_16x16x32_bf16 v[134:137], v[238:241], v[182:185], v[134:137]
	v_mfma_f32_16x16x32_bf16 v[138:141], v[238:241], v[186:189], v[138:141]
	s_waitcnt lgkmcnt(3)
	v_mfma_f32_16x16x32_bf16 v[142:145], v[238:241], v[190:193], v[142:145]
	s_waitcnt lgkmcnt(2)
	v_mfma_f32_16x16x32_bf16 v[162:165], v[202:205], v[178:181], v[162:165]
	v_mfma_f32_16x16x32_bf16 v[166:169], v[202:205], v[182:185], v[166:169]
	v_mfma_f32_16x16x32_bf16 v[170:173], v[202:205], v[186:189], v[170:173]
	v_mfma_f32_16x16x32_bf16 v[174:177], v[202:205], v[190:193], v[174:177]
	ds_read_b128 v[202:205], v217 offset:8192
	s_waitcnt lgkmcnt(2)
	v_mfma_f32_16x16x32_bf16 v[146:149], v[198:201], v[178:181], v[146:149]
	v_mfma_f32_16x16x32_bf16 v[150:153], v[198:201], v[182:185], v[150:153]
	v_mfma_f32_16x16x32_bf16 v[154:157], v[198:201], v[186:189], v[154:157]
	v_mfma_f32_16x16x32_bf16 v[158:161], v[198:201], v[190:193], v[158:161]
	ds_read_b128 v[198:201], v217 offset:10240
	s_waitcnt lgkmcnt(2)
	v_mfma_f32_16x16x32_bf16 v[118:121], v[194:197], v[178:181], v[118:121]
	v_mfma_f32_16x16x32_bf16 v[122:125], v[194:197], v[182:185], v[122:125]
	v_mfma_f32_16x16x32_bf16 v[126:129], v[194:197], v[186:189], v[126:129]
	v_mfma_f32_16x16x32_bf16 v[130:133], v[194:197], v[190:193], v[130:133]
	ds_read_b128 v[194:197], v217 offset:12288
	s_waitcnt lgkmcnt(2)
	v_mfma_f32_16x16x32_bf16 v[98:101], v[202:205], v[178:181], v[98:101]
	v_mfma_f32_16x16x32_bf16 v[102:105], v[202:205], v[182:185], v[102:105]
	v_mfma_f32_16x16x32_bf16 v[106:109], v[202:205], v[186:189], v[106:109]
	v_mfma_f32_16x16x32_bf16 v[110:113], v[202:205], v[190:193], v[110:113]
	ds_read_b128 v[202:205], v217 offset:14336
	s_waitcnt lgkmcnt(2)
	v_mfma_f32_16x16x32_bf16 v[82:85], v[198:201], v[178:181], v[82:85]
	v_mfma_f32_16x16x32_bf16 v[86:89], v[198:201], v[182:185], v[86:89]
	v_mfma_f32_16x16x32_bf16 v[90:93], v[198:201], v[186:189], v[90:93]
	v_mfma_f32_16x16x32_bf16 v[94:97], v[198:201], v[190:193], v[94:97]
	s_waitcnt lgkmcnt(1)
	v_mfma_f32_16x16x32_bf16 v[66:69], v[194:197], v[178:181], v[66:69]
	v_mfma_f32_16x16x32_bf16 v[70:73], v[194:197], v[182:185], v[70:73]
	v_mfma_f32_16x16x32_bf16 v[74:77], v[194:197], v[186:189], v[74:77]
	v_mfma_f32_16x16x32_bf16 v[78:81], v[194:197], v[190:193], v[78:81]
	s_waitcnt lgkmcnt(0)
	v_mfma_f32_16x16x32_bf16 v[50:53], v[202:205], v[178:181], v[50:53]
	v_mfma_f32_16x16x32_bf16 v[54:57], v[202:205], v[182:185], v[54:57]
	v_mfma_f32_16x16x32_bf16 v[58:61], v[202:205], v[186:189], v[58:61]
	v_mfma_f32_16x16x32_bf16 v[62:65], v[202:205], v[190:193], v[62:65]
	s_setprio 0
	s_branch .LBB0_1686

.LBB0_1817:
	s_waitcnt lgkmcnt(3)
	v_mfma_f32_16x16x32_bf16 v[174:177], v[178:181], v[194:197], v[174:177]
	v_mfma_f32_16x16x32_bf16 v[170:173], v[178:181], v[198:201], v[170:173]
	v_mfma_f32_16x16x32_bf16 v[166:169], v[178:181], v[218:221], v[166:169]
	v_mfma_f32_16x16x32_bf16 v[158:161], v[178:181], v[226:229], v[158:161]
	s_add_u32 s100, s36, 0xc5cc000
	s_addc_u32 s101, s37, 0
	global_load_dwordx4 v[98:101], v208, s[100:101] offset:128
	v_add_u32_e32 v102, 0x2c000, v208
	global_load_dwordx4 v[102:105], v102, s[100:101] offset:128
	ds_read_b128 v[202:205], v216 offset:8192
	s_waitcnt lgkmcnt(3)
	v_mfma_f32_16x16x32_bf16 v[162:165], v[182:185], v[194:197], v[162:165]
	v_mfma_f32_16x16x32_bf16 v[154:157], v[182:185], v[198:201], v[154:157]
	v_mfma_f32_16x16x32_bf16 v[118:121], v[182:185], v[218:221], v[118:121]
	v_mfma_f32_16x16x32_bf16 v[106:109], v[182:185], v[226:229], v[106:109]
	v_add_u32_e32 v110, 0x58000, v208
	global_load_dwordx4 v[110:113], v110, s[100:101] offset:128
	v_add_u32_e32 v114, 0x84000, v208
	global_load_dwordx4 v[114:117], v114, s[100:101] offset:128
	v_add_u32_e32 v217, v214, v212
	ds_read_b128 v[238:241], v216 offset:10240
	ds_read_b128 v[178:181], v217 offset:32768
	s_waitcnt lgkmcnt(4)
	v_mfma_f32_16x16x32_bf16 v[94:97], v[186:189], v[194:197], v[94:97]
	v_mfma_f32_16x16x32_bf16 v[90:93], v[186:189], v[198:201], v[90:93]
	v_mfma_f32_16x16x32_bf16 v[86:89], v[186:189], v[218:221], v[86:89]
	v_mfma_f32_16x16x32_bf16 v[82:85], v[186:189], v[226:229], v[82:85]
	v_add_u32_e32 v122, 0xb0000, v208
	global_load_dwordx4 v[122:125], v122, s[100:101] offset:128
	v_add_u32_e32 v130, 0xdc000, v208
	global_load_dwordx4 v[130:133], v130, s[100:101] offset:128
	ds_read_b128 v[242:245], v216 offset:12288
	ds_read_b128 v[182:185], v217 offset:34816
	s_waitcnt lgkmcnt(5)
	v_mfma_f32_16x16x32_bf16 v[78:81], v[190:193], v[194:197], v[78:81]
	v_mfma_f32_16x16x32_bf16 v[74:77], v[190:193], v[198:201], v[74:77]
	v_mfma_f32_16x16x32_bf16 v[70:73], v[190:193], v[218:221], v[70:73]
	v_mfma_f32_16x16x32_bf16 v[66:69], v[190:193], v[226:229], v[66:69]
	v_add_u32_e32 v138, 0x108000, v208
	global_load_dwordx4 v[138:141], v138, s[100:101] offset:128
	v_add_u32_e32 v146, 0x134000, v208
	global_load_dwordx4 v[146:149], v146, s[100:101] offset:128
	ds_read_b128 v[246:249], v216 offset:14336
	ds_read_b128 v[186:189], v217 offset:36864
	s_waitcnt lgkmcnt(6)
	v_mfma_f32_16x16x32_bf16 v[62:65], v[202:205], v[194:197], v[62:65]
	v_mfma_f32_16x16x32_bf16 v[58:61], v[202:205], v[198:201], v[58:61]
	v_mfma_f32_16x16x32_bf16 v[54:57], v[202:205], v[218:221], v[54:57]
	v_mfma_f32_16x16x32_bf16 v[50:53], v[202:205], v[226:229], v[50:53]
	s_add_u32 s100, s38, 0xc04c000
	s_addc_u32 s101, s39, 0
	global_load_dwordx4 v[126:129], v208, s[100:101] offset:128
	v_add_u32_e32 v134, 0x2c000, v208
	global_load_dwordx4 v[134:137], v134, s[100:101] offset:128
	v_add_u32_e32 v216, v213, v212
	s_waitcnt lgkmcnt(5)
	v_mfma_f32_16x16x32_bf16 v[46:49], v[238:241], v[194:197], v[46:49]
	v_mfma_f32_16x16x32_bf16 v[42:45], v[238:241], v[198:201], v[42:45]
	v_mfma_f32_16x16x32_bf16 v[38:41], v[238:241], v[218:221], v[38:41]
	v_mfma_f32_16x16x32_bf16 v[34:37], v[238:241], v[226:229], v[34:37]
	v_add_u32_e32 v142, 0x58000, v208
	global_load_dwordx4 v[142:145], v142, s[100:101] offset:128
	v_add_u32_e32 v150, 0x84000, v208
	global_load_dwordx4 v[150:153], v150, s[100:101] offset:128
	ds_read_b128 v[238:241], v216
	ds_read_b128 v[190:193], v217 offset:38912
	ds_read_b128 v[202:205], v216 offset:2048
	s_waitcnt lgkmcnt(6)
	v_mfma_f32_16x16x32_bf16 v[30:33], v[242:245], v[194:197], v[30:33]
	v_mfma_f32_16x16x32_bf16 v[26:29], v[242:245], v[198:201], v[26:29]
	v_mfma_f32_16x16x32_bf16 v[18:21], v[242:245], v[218:221], v[18:21]
	v_mfma_f32_16x16x32_bf16 v[6:9], v[242:245], v[226:229], v[6:9]
	s_waitcnt lgkmcnt(4)
	v_mfma_f32_16x16x32_bf16 v[14:17], v[246:249], v[198:201], v[14:17]
	ds_read_b128 v[198:201], v216 offset:4096
	v_mfma_f32_16x16x32_bf16 v[22:25], v[246:249], v[194:197], v[22:25]
	v_mfma_f32_16x16x32_bf16 v[10:13], v[246:249], v[218:221], v[10:13]
	v_mfma_f32_16x16x32_bf16 v[2:5], v[246:249], v[226:229], v[2:5]
	ds_read_b128 v[194:197], v216 offset:6144
	s_waitcnt lgkmcnt(4)
	v_mfma_f32_16x16x32_bf16 v[174:177], v[238:241], v[178:181], v[174:177]
	v_mfma_f32_16x16x32_bf16 v[170:173], v[238:241], v[182:185], v[170:173]
	v_mfma_f32_16x16x32_bf16 v[166:169], v[238:241], v[186:189], v[166:169]
	s_waitcnt lgkmcnt(3)
	v_mfma_f32_16x16x32_bf16 v[158:161], v[238:241], v[190:193], v[158:161]
	s_branch .LBB0_1814
.Lpeel_1814:
	s_waitcnt lgkmcnt(3)
	v_mfma_f32_16x16x32_bf16 v[174:177], v[178:181], v[194:197], v[174:177]
	v_mfma_f32_16x16x32_bf16 v[170:173], v[178:181], v[198:201], v[170:173]
	v_mfma_f32_16x16x32_bf16 v[166:169], v[178:181], v[218:221], v[166:169]
	v_mfma_f32_16x16x32_bf16 v[158:161], v[178:181], v[226:229], v[158:161]
	ds_read_b128 v[202:205], v216 offset:8192
	s_waitcnt lgkmcnt(3)
	v_mfma_f32_16x16x32_bf16 v[162:165], v[182:185], v[194:197], v[162:165]
	v_mfma_f32_16x16x32_bf16 v[154:157], v[182:185], v[198:201], v[154:157]
	v_mfma_f32_16x16x32_bf16 v[118:121], v[182:185], v[218:221], v[118:121]
	v_mfma_f32_16x16x32_bf16 v[106:109], v[182:185], v[226:229], v[106:109]
	v_add_u32_e32 v217, v214, v212
	ds_read_b128 v[238:241], v216 offset:10240
	ds_read_b128 v[178:181], v217 offset:32768
	s_waitcnt lgkmcnt(4)
	v_mfma_f32_16x16x32_bf16 v[94:97], v[186:189], v[194:197], v[94:97]
	v_mfma_f32_16x16x32_bf16 v[90:93], v[186:189], v[198:201], v[90:93]
	v_mfma_f32_16x16x32_bf16 v[86:89], v[186:189], v[218:221], v[86:89]
	v_mfma_f32_16x16x32_bf16 v[82:85], v[186:189], v[226:229], v[82:85]
	ds_read_b128 v[242:245], v216 offset:12288
	ds_read_b128 v[182:185], v217 offset:34816
	s_waitcnt lgkmcnt(5)
	v_mfma_f32_16x16x32_bf16 v[78:81], v[190:193], v[194:197], v[78:81]
	v_mfma_f32_16x16x32_bf16 v[74:77], v[190:193], v[198:201], v[74:77]
	v_mfma_f32_16x16x32_bf16 v[70:73], v[190:193], v[218:221], v[70:73]
	v_mfma_f32_16x16x32_bf16 v[66:69], v[190:193], v[226:229], v[66:69]
	ds_read_b128 v[246:249], v216 offset:14336
	ds_read_b128 v[186:189], v217 offset:36864
	s_waitcnt lgkmcnt(6)
	v_mfma_f32_16x16x32_bf16 v[62:65], v[202:205], v[194:197], v[62:65]
	v_mfma_f32_16x16x32_bf16 v[58:61], v[202:205], v[198:201], v[58:61]
	v_mfma_f32_16x16x32_bf16 v[54:57], v[202:205], v[218:221], v[54:57]
	v_mfma_f32_16x16x32_bf16 v[50:53], v[202:205], v[226:229], v[50:53]
	v_add_u32_e32 v216, v213, v212
	s_waitcnt lgkmcnt(5)
	v_mfma_f32_16x16x32_bf16 v[46:49], v[238:241], v[194:197], v[46:49]
	v_mfma_f32_16x16x32_bf16 v[42:45], v[238:241], v[198:201], v[42:45]
	v_mfma_f32_16x16x32_bf16 v[38:41], v[238:241], v[218:221], v[38:41]
	v_mfma_f32_16x16x32_bf16 v[34:37], v[238:241], v[226:229], v[34:37]
	ds_read_b128 v[238:241], v216
	ds_read_b128 v[190:193], v217 offset:38912
	ds_read_b128 v[202:205], v216 offset:2048
	s_waitcnt lgkmcnt(6)
	v_mfma_f32_16x16x32_bf16 v[30:33], v[242:245], v[194:197], v[30:33]
	v_mfma_f32_16x16x32_bf16 v[26:29], v[242:245], v[198:201], v[26:29]
	v_mfma_f32_16x16x32_bf16 v[18:21], v[242:245], v[218:221], v[18:21]
	v_mfma_f32_16x16x32_bf16 v[6:9], v[242:245], v[226:229], v[6:9]
	s_waitcnt lgkmcnt(4)
	v_mfma_f32_16x16x32_bf16 v[14:17], v[246:249], v[198:201], v[14:17]
	ds_read_b128 v[198:201], v216 offset:4096
	v_mfma_f32_16x16x32_bf16 v[22:25], v[246:249], v[194:197], v[22:25]
	v_mfma_f32_16x16x32_bf16 v[10:13], v[246:249], v[218:221], v[10:13]
	v_mfma_f32_16x16x32_bf16 v[2:5], v[246:249], v[226:229], v[2:5]
	ds_read_b128 v[194:197], v216 offset:6144
	s_waitcnt lgkmcnt(4)
	v_mfma_f32_16x16x32_bf16 v[174:177], v[238:241], v[178:181], v[174:177]
	v_mfma_f32_16x16x32_bf16 v[170:173], v[238:241], v[182:185], v[170:173]
	v_mfma_f32_16x16x32_bf16 v[166:169], v[238:241], v[186:189], v[166:169]
	s_waitcnt lgkmcnt(3)
	v_mfma_f32_16x16x32_bf16 v[158:161], v[238:241], v[190:193], v[158:161]
	s_add_i32 s20, s20, 64
	s_waitcnt lgkmcnt(2)
	v_mfma_f32_16x16x32_bf16 v[162:165], v[202:205], v[178:181], v[162:165]
	v_mfma_f32_16x16x32_bf16 v[154:157], v[202:205], v[182:185], v[154:157]
	v_mfma_f32_16x16x32_bf16 v[118:121], v[202:205], v[186:189], v[118:121]
	v_mfma_f32_16x16x32_bf16 v[106:109], v[202:205], v[190:193], v[106:109]
	ds_read_b128 v[202:205], v216 offset:8192
	s_waitcnt lgkmcnt(2)
	v_mfma_f32_16x16x32_bf16 v[94:97], v[198:201], v[178:181], v[94:97]
	v_mfma_f32_16x16x32_bf16 v[90:93], v[198:201], v[182:185], v[90:93]
	v_mfma_f32_16x16x32_bf16 v[86:89], v[198:201], v[186:189], v[86:89]
	v_mfma_f32_16x16x32_bf16 v[82:85], v[198:201], v[190:193], v[82:85]
	ds_read_b128 v[198:201], v216 offset:10240
	s_waitcnt lgkmcnt(2)
	v_mfma_f32_16x16x32_bf16 v[78:81], v[194:197], v[178:181], v[78:81]
	v_mfma_f32_16x16x32_bf16 v[74:77], v[194:197], v[182:185], v[74:77]
	v_mfma_f32_16x16x32_bf16 v[70:73], v[194:197], v[186:189], v[70:73]
	v_mfma_f32_16x16x32_bf16 v[66:69], v[194:197], v[190:193], v[66:69]
	ds_read_b128 v[194:197], v216 offset:12288
	s_waitcnt lgkmcnt(2)
	v_mfma_f32_16x16x32_bf16 v[62:65], v[202:205], v[178:181], v[62:65]
	v_mfma_f32_16x16x32_bf16 v[58:61], v[202:205], v[182:185], v[58:61]
	v_mfma_f32_16x16x32_bf16 v[54:57], v[202:205], v[186:189], v[54:57]
	v_mfma_f32_16x16x32_bf16 v[50:53], v[202:205], v[190:193], v[50:53]
	ds_read_b128 v[202:205], v216 offset:14336
	s_waitcnt lgkmcnt(2)
	v_mfma_f32_16x16x32_bf16 v[46:49], v[198:201], v[178:181], v[46:49]
	v_mfma_f32_16x16x32_bf16 v[42:45], v[198:201], v[182:185], v[42:45]
	v_mfma_f32_16x16x32_bf16 v[38:41], v[198:201], v[186:189], v[38:41]
	v_mfma_f32_16x16x32_bf16 v[34:37], v[198:201], v[190:193], v[34:37]
	s_waitcnt lgkmcnt(1)
	v_mfma_f32_16x16x32_bf16 v[30:33], v[194:197], v[178:181], v[30:33]
	v_mfma_f32_16x16x32_bf16 v[26:29], v[194:197], v[182:185], v[26:29]
	v_mfma_f32_16x16x32_bf16 v[18:21], v[194:197], v[186:189], v[18:21]
	v_mfma_f32_16x16x32_bf16 v[6:9], v[194:197], v[190:193], v[6:9]
	s_waitcnt lgkmcnt(0)
	v_mfma_f32_16x16x32_bf16 v[22:25], v[202:205], v[178:181], v[22:25]
	v_mfma_f32_16x16x32_bf16 v[14:17], v[202:205], v[182:185], v[14:17]
	v_mfma_f32_16x16x32_bf16 v[10:13], v[202:205], v[186:189], v[10:13]
	v_mfma_f32_16x16x32_bf16 v[2:5], v[202:205], v[190:193], v[2:5]
	s_setprio 0
	s_branch .LBB0_1821
